# indexer score loop hand-rewritten: 2-tile-ahead coalesced prefetch, LDS transposes woven into the VALU body, trimmed bit-identical VALU
# speedup vs baseline: 1.0106x; 1.0106x over previous
; __device__ __forceinline__ void indexer_phase(const bf16_t* PJ, float* rk, unsigned short* SEL, LAS unsigned char* lds) {
;     ...
;         const int b = gl >> 9, jj = gl & 511, t0 = (jj < 256 ? jj : 767 - jj) * 8;
;         const size_t rowbase = (size_t)b * SEQ;
;         const int t = t0 + wid;
;         unsigned short* selrow = SEL + (rowbase + t) * 256;
;         if (t0 + 7 < 256) {
; #pragma unroll
;             for (int i = 0; i < 4; ++i) { const int s = lane + 64 * i; selrow[s] = (unsigned short)(s <= t ? s : 0); }
;             continue;
;         }
;         {
;             const int g = r32 >> 3, hp = (r32 >> 2) & 1, ii = r32 & 3, tq = 2 * hp + (g >> 1), head = 4 * (g & 1) + ii;
;             bf16x8 af[2][4]; float wq[2][2][8];
; #pragma unroll
;             for (int rt = 0; rt < 2; ++rt) {
;                 const bf16_t* qp = PJ + (rowbase + t0 + 4 * rt + tq) * PROJ_LD + PJ_QI + head * 64 + hi * 8;
; #pragma unroll
;                 for (int kk = 0; kk < 4; ++kk) af[rt][kk] = *(const bf16x8*)(qp + kk * 16);
; #pragma unroll
;                 for (int qq = 0; qq < 2; ++qq) { const u32x4 w = *(const u32x4*)(PJ + (rowbase + t0 + 4 * rt + 2 * hi + qq) * PROJ_LD + PJ_WI);
;                     const float sc = 0.35355339059327373f;
;                     wq[rt][qq][0] = bflo(w.x) * sc; wq[rt][qq][1] = bfhi(w.x) * sc; wq[rt][qq][2] = bflo(w.y) * sc; wq[rt][qq][3] = bfhi(w.y) * sc;
;                     wq[rt][qq][4] = bflo(w.z) * sc; wq[rt][qq][5] = bfhi(w.z) * sc; wq[rt][qq][6] = bflo(w.w) * sc; wq[rt][qq][7] = bfhi(w.w) * sc; }
;             }
;             float rmax[2][2], rmin[2][2];
; #pragma unroll
;             for (int rt = 0; rt < 2; ++rt)
; #pragma unroll
;                 for (int qq = 0; qq < 2; ++qq) { rmax[rt][qq] = -INFINITY; rmin[rt][qq] = INFINITY; }
;             const int nkt = (t0 + 8 + 31) >> 5;
;             const bf16_t* kbase = PJ + (rowbase + r32) * PROJ_LD + PJ_KI + hi * 8;
;             bf16x8 bcur[4], bnxt[4];
;             int kt = wid;
; #pragma unroll
;             for (int kk = 0; kk < 4; ++kk) bcur[kk] = *(const bf16x8*)(kbase + (size_t)(32 * kt) * PROJ_LD + kk * 16);
.LBB0_864:
	s_and_b32 s0, s2, 0x1ff
	s_ashr_i32 s24, s2, 9
	s_sub_i32 s1, 0x2ff, s0
	s_cmpk_lt_u32 s0, 0x100
	s_cselect_b32 s0, s0, s1
	s_lshl_b32 s1, s0, 3
	s_ashr_i32 s25, s24, 31
	s_add_i32 s77, s1, s33
	s_lshl_b64 s[26:27], s[24:25], 12
	s_ashr_i32 s3, s77, 31
	s_add_u32 s24, s26, s77
	s_addc_u32 s25, s27, s3
	s_lshl_b64 s[24:25], s[24:25], 9
	s_add_u32 s60, s4, s24
	s_addc_u32 s61, s5, s25
	s_cmp_gt_u32 s0, 31
	s_mov_b64 s[24:25], -1
	s_cbranch_scc0 .LBB0_1027
	s_add_i32 s0, s1, 39
	s_lshr_b32 s0, s0, 5
	s_cmp_ge_i32 s33, s0
	s_cbranch_scc1 .LBB0_873
	v_readlane_b32 s24, v255, 13
	s_add_u32 s3, s26, s1
	v_readlane_b32 s25, v255, 14
	v_or_b32_e32 v0, s3, v112
	s_addc_u32 s6, s27, 0
	v_mov_b64_e32 v[16:17], s[24:25]
	v_mad_u64_u32 v[0:1], s[24:25], v0, s7, v[16:17]
	v_mad_i32_i24 v1, s6, v177, v1
	v_lshl_add_u64 v[0:1], v[0:1], 0, v[114:115]
	v_mov_b32_e32 v123, v115
	v_lshl_add_u64 v[18:19], v[0:1], 0, v[122:123]
	v_or_b32_e32 v0, s3, v116
	v_add_co_u32_e32 v20, vcc, s44, v18
	v_mad_u64_u32 v[0:1], s[24:25], v0, s7, v[16:17]
	v_mad_i32_i24 v1, s6, v177, v1
	s_mov_b64 s[24:25], vcc
	v_add_co_u32_e32 v0, vcc, s44, v0
	v_or_b32_e32 v4, s3, v120
	s_nop 0
	v_addc_co_u32_e32 v1, vcc, 0, v1, vcc
	v_mad_u64_u32 v[4:5], s[28:29], v4, s7, v[16:17]
	s_or_b32 s3, s3, 4
	v_mad_i32_i24 v5, s6, v177, v5
	v_add_co_u32_e32 v4, vcc, s44, v4
	v_or_b32_e32 v8, s3, v116
	s_nop 0
	v_addc_co_u32_e32 v5, vcc, 0, v5, vcc
	v_mad_u64_u32 v[8:9], s[28:29], v8, s7, v[16:17]
	v_mad_i32_i24 v9, s6, v177, v9
	v_add_co_u32_e32 v8, vcc, s44, v8
	v_or_b32_e32 v12, s3, v120
	s_nop 0
	v_addc_co_u32_e32 v9, vcc, 0, v9, vcc
	s_mov_b64 s[30:31], 0x1100
	s_waitcnt lgkmcnt(0)
	v_mad_u64_u32 v[12:13], s[28:29], v12, s7, v[16:17]
	v_lshl_add_u64 v[22:23], v[18:19], 0, s[30:31]
	v_mad_i32_i24 v13, s6, v177, v13
	v_add_co_u32_e32 v12, vcc, s44, v12
	v_or_b32_e32 v18, s3, v112
	global_load_dwordx4 v[0:3], v[0:1], off offset:1408
	v_addc_co_u32_e32 v13, vcc, 0, v13, vcc
	v_addc_co_u32_e64 v21, vcc, 0, v19, s[24:25]
	v_mad_u64_u32 v[18:19], s[24:25], v18, s7, v[16:17]
	v_mad_i32_i24 v19, s6, v177, v19
	global_load_dwordx4 v[4:7], v[4:5], off offset:1408
	v_lshl_add_u64 v[18:19], v[18:19], 0, v[114:115]
	v_lshl_add_u64 v[18:19], v[18:19], 0, v[122:123]
	global_load_dwordx4 v[8:11], v[8:9], off offset:1408
	v_or_b32_e32 v190, s1, v116
	global_load_dwordx4 v[12:15], v[12:13], off offset:1408
	s_nop 0
	global_load_dwordx4 v[64:67], v[22:23], off offset:32
	global_load_dwordx4 v[68:71], v[22:23], off offset:64
	global_load_dwordx4 v[72:75], v[20:21], off offset:256
	global_load_dwordx4 v[76:79], v[22:23], off offset:96
	v_lshl_add_u64 v[20:21], v[18:19], 0, s[30:31]
	v_add_co_u32_e32 v22, vcc, s44, v18
	v_or_b32_e32 v18, s26, v110
	v_mad_u64_u32 v[16:17], s[24:25], v18, s7, v[16:17]
	v_mad_i32_i24 v17, s27, v177, v17
	v_lshl_add_u64 v[16:17], v[16:17], 0, v[122:123]
	s_mov_b64 s[24:25], 0x1500
	v_lshl_add_u64 v[124:125], v[16:17], 0, s[24:25]
	v_lshl_add_u64 v[216:217], v[218:219], 0, v[124:125]
	v_readlane_b32 s24, v255, 21
	v_readlane_b32 s25, v255, 22
	v_addc_co_u32_e32 v23, vcc, 0, v19, vcc
	s_nop 0
	v_lshl_add_u64 v[16:17], v[124:125], 0, s[24:25]
	global_load_dwordx4 v[80:83], v[20:21], off offset:32
	global_load_dwordx4 v[84:87], v[20:21], off offset:64
	global_load_dwordx4 v[96:99], v[16:17], off offset:96
	global_load_dwordx4 v[100:103], v[16:17], off offset:64
	global_load_dwordx4 v[104:107], v[16:17], off offset:32
	s_nop 0
	global_load_dwordx4 v[244:247], v[16:17], off
	s_nop 0
	global_load_dwordx4 v[88:91], v[22:23], off offset:256
	global_load_dwordx4 v[92:95], v[20:21], off offset:96
	v_mov_b64_e32 v[54:55], v[34:35]
	v_mov_b64_e32 v[58:59], v[38:39]
	v_mov_b64_e32 v[62:63], v[42:43]
	v_mov_b64_e32 v[50:51], v[46:47]
	v_or_b32_e32 v191, 1, v190
	v_or_b32_e32 v192, 4, v190
	v_or_b32_e32 v193, 5, v190
	v_mov_b32_e32 v189, 0xff800000
	v_mov_b32_e32 v188, 0x7f800000
	v_mov_b32_e32 v196, v171
	v_readlane_b32 s6, v255, 20
	v_mov_b64_e32 v[52:53], v[32:33]
	v_mov_b64_e32 v[56:57], v[36:37]
	v_mov_b64_e32 v[60:61], v[40:41]
	v_mov_b64_e32 v[48:49], v[44:45]
	v_mov_b32_e32 v186, 0x7f800000
	v_mov_b32_e32 v184, 0x7f800000
	v_mov_b32_e32 v123, 0x7f800000
	v_mov_b32_e32 v187, 0xff800000
	v_mov_b32_e32 v185, 0xff800000
	v_mov_b32_e32 v183, 0xff800000
	s_mov_b32 s1, s33
	s_waitcnt vmcnt(15)
	v_and_b32_e32 v20, 0xffff0000, v0
	v_lshlrev_b32_e32 v21, 16, v0
	v_and_b32_e32 v0, 0xffff0000, v1
	v_lshlrev_b32_e32 v1, 16, v1
	v_pk_mul_f32 v[128:129], v[0:1], s[58:59] op_sel_hi:[1,0]
	v_and_b32_e32 v0, 0xffff0000, v3
	v_lshlrev_b32_e32 v1, 16, v3
	v_pk_mul_f32 v[132:133], v[0:1], s[58:59] op_sel_hi:[1,0]
	s_waitcnt vmcnt(14)
	v_and_b32_e32 v0, 0xffff0000, v4
	v_lshlrev_b32_e32 v1, 16, v4
	v_pk_mul_f32 v[134:135], v[0:1], s[58:59] op_sel_hi:[1,0]
	v_and_b32_e32 v0, 0xffff0000, v5
	v_lshlrev_b32_e32 v1, 16, v5
	v_pk_mul_f32 v[136:137], v[0:1], s[58:59] op_sel_hi:[1,0]
	v_and_b32_e32 v0, 0xffff0000, v6
	v_lshlrev_b32_e32 v1, 16, v6
	v_pk_mul_f32 v[138:139], v[0:1], s[58:59] op_sel_hi:[1,0]
	v_and_b32_e32 v0, 0xffff0000, v7
	v_lshlrev_b32_e32 v1, 16, v7
	v_pk_mul_f32 v[140:141], v[0:1], s[58:59] op_sel_hi:[1,0]
	s_waitcnt vmcnt(13)
	v_and_b32_e32 v0, 0xffff0000, v8
	v_lshlrev_b32_e32 v1, 16, v8
	v_pk_mul_f32 v[142:143], v[0:1], s[58:59] op_sel_hi:[1,0]
	v_and_b32_e32 v0, 0xffff0000, v9
	v_lshlrev_b32_e32 v1, 16, v9
	v_pk_mul_f32 v[144:145], v[0:1], s[58:59] op_sel_hi:[1,0]
	v_and_b32_e32 v0, 0xffff0000, v10
	v_lshlrev_b32_e32 v1, 16, v10
	v_pk_mul_f32 v[146:147], v[0:1], s[58:59] op_sel_hi:[1,0]
	v_and_b32_e32 v0, 0xffff0000, v11
	v_lshlrev_b32_e32 v1, 16, v11
	v_pk_mul_f32 v[148:149], v[0:1], s[58:59] op_sel_hi:[1,0]
	s_waitcnt vmcnt(12)
	v_and_b32_e32 v0, 0xffff0000, v12
	v_lshlrev_b32_e32 v1, 16, v12
	v_pk_mul_f32 v[150:151], v[0:1], s[58:59] op_sel_hi:[1,0]
	v_and_b32_e32 v0, 0xffff0000, v13
	v_lshlrev_b32_e32 v1, 16, v13
	v_pk_mul_f32 v[152:153], v[0:1], s[58:59] op_sel_hi:[1,0]
	v_and_b32_e32 v0, 0xffff0000, v14
	v_lshlrev_b32_e32 v1, 16, v14
	v_and_b32_e32 v22, 0xffff0000, v2
	v_lshlrev_b32_e32 v23, 16, v2
	v_pk_mul_f32 v[154:155], v[0:1], s[58:59] op_sel_hi:[1,0]
	v_and_b32_e32 v0, 0xffff0000, v15
	v_lshlrev_b32_e32 v1, 16, v15
	v_pk_mul_f32 v[126:127], v[20:21], s[58:59] op_sel_hi:[1,0]
	v_pk_mul_f32 v[130:131], v[22:23], s[58:59] op_sel_hi:[1,0]
	v_pk_mul_f32 v[156:157], v[0:1], s[58:59] op_sel_hi:[1,0]
	s_waitcnt vmcnt(0)
	s_add_i32 s32, s1, 8
	s_cmp_lt_i32 s32, s0
	s_cbranch_scc0 .Lidx_loopA
	s_add_i32 s32, s6, 0x100
	v_mad_i64_i32 v[0:1], s[26:27], s32, v177, v[216:217]
	s_add_i32 s32, s32, 16
	v_mad_i64_i32 v[220:221], s[26:27], s32, v177, v[216:217]
	global_load_dwordx4 v[52:55], v[0:1], off
	global_load_dwordx4 v[56:59], v[220:221], off
	global_load_dwordx4 v[60:63], v[0:1], off offset:64
	global_load_dwordx4 v[48:51], v[220:221], off offset:64
; #define LAS __attribute__((address_space(3)))
; __device__ __forceinline__ void indexer_phase(const bf16_t* PJ, float* rk, unsigned short* SEL, LAS unsigned char* lds) {
;     ...
;             while (kt < nkt) {
;                 const int kn = kt + NWAVE;
;                 if (kn < nkt) {
; #pragma unroll
;                     for (int kk = 0; kk < 4; ++kk) bnxt[kk] = *(const bf16x8*)(kbase + (size_t)(32 * kn) * PROJ_LD + kk * 16);
;                 }
;                 const int key = 32 * kt + r32;
; #pragma unroll
;                 for (int rt = 0; rt < 2; ++rt) {
;                     f32x16 acc = f32x16{};
; #pragma unroll
;                     for (int kk = 0; kk < 4; ++kk) acc = __builtin_amdgcn_mfma_f32_32x32x16_bf16(af[rt][kk], bcur[kk], acc, 0, 0, 0);
; #pragma unroll
;                     for (int qq = 0; qq < 2; ++qq) { float s = 0.f;
; #pragma unroll
;                         for (int e = 0; e < 8; ++e) s += wq[rt][qq][e] * fmaxf(acc[8 * qq + e], 0.f);
;                         ((LAS float*)lds)[(4 * rt + 2 * hi + qq) * 4096 + key] = s;
;                         const bool ok = key <= t0 + 4 * rt + 2 * hi + qq;
;                         rmax[rt][qq] = fmaxf(rmax[rt][qq], ok ? s : -INFINITY); rmin[rt][qq] = fminf(rmin[rt][qq], ok ? s : INFINITY); }
.Lidx_loopA:
	s_add_i32 s1, s1, 8
	s_cmp_ge_i32 s1, s0
	s_cselect_b64 s[24:25], -1, 0
	s_add_i32 s3, s6, 0x100
	s_add_i32 s32, s1, 8
	s_cmp_lt_i32 s32, s0
	s_cbranch_scc0 .Lidx_nofarA
	s_add_i32 s32, s6, 0x200
	v_mad_i64_i32 v[0:1], s[26:27], s32, v177, v[216:217]
	s_add_i32 s32, s32, 16
	v_mad_i64_i32 v[220:221], s[26:27], s32, v177, v[216:217]
	global_load_dwordx4 v[228:231], v[0:1], off
	global_load_dwordx4 v[232:235], v[220:221], off
	global_load_dwordx4 v[236:239], v[0:1], off offset:64
	global_load_dwordx4 v[240:243], v[220:221], off offset:64
.Lidx_nofarA:
	s_waitcnt lgkmcnt(0)
	v_mfma_f32_32x32x16_bf16 v[0:15], v[72:75], v[244:247], 0
	v_add_u32_e32 v197, s6, v110
	v_mfma_f32_32x32x16_bf16 v[0:15], v[64:67], v[104:107], v[0:15]
	v_mfma_f32_32x32x16_bf16 v[0:15], v[68:71], v[100:103], v[0:15]
	v_mfma_f32_32x32x16_bf16 v[0:15], v[76:79], v[96:99], v[0:15]
	v_mfma_f32_32x32x16_bf16 v[16:31], v[88:91], v[244:247], 0
	v_mfma_f32_32x32x16_bf16 v[16:31], v[80:83], v[104:107], v[16:31]
	v_mfma_f32_32x32x16_bf16 v[16:31], v[84:87], v[100:103], v[16:31]
	v_mfma_f32_32x32x16_bf16 v[16:31], v[92:95], v[96:99], v[16:31]
	s_add_i32 s32, s1, 8
	s_cmp_lt_i32 s32, s0
	s_cbranch_scc1 .Lidx_w4A
	s_waitcnt vmcnt(0)
	s_branch .Lidx_trA
.Lidx_w4A:
	s_waitcnt vmcnt(4)
.Lidx_trA:
	ds_write_b128 v222, v[52:55]
	ds_write_b128 v222, v[56:59] offset:1024
	s_nop 3
	v_max_f32_e32 v0, 0, v0
	v_max_f32_e32 v1, 0, v1
	v_pk_mul_f32 v[0:1], v[126:127], v[0:1] op_sel:[1,0] op_sel_hi:[0,1]
	v_max_f32_e32 v2, 0, v2
	v_max_f32_e32 v3, 0, v3
	v_pk_mul_f32 v[2:3], v[128:129], v[2:3] op_sel:[1,0] op_sel_hi:[0,1]
	v_max_f32_e32 v4, 0, v4
	v_max_f32_e32 v5, 0, v5
	v_pk_mul_f32 v[4:5], v[130:131], v[4:5] op_sel:[1,0] op_sel_hi:[0,1]
	v_max_f32_e32 v6, 0, v6
	v_max_f32_e32 v7, 0, v7
	v_pk_mul_f32 v[6:7], v[132:133], v[6:7] op_sel:[1,0] op_sel_hi:[0,1]
	v_add_f32_e32 v0, 0, v0
	v_max_f32_e32 v8, 0, v8
	v_add_f32_e32 v0, v1, v0
	v_max_f32_e32 v9, 0, v9
	v_add_f32_e32 v0, v2, v0
	v_pk_mul_f32 v[8:9], v[134:135], v[8:9] op_sel:[1,0] op_sel_hi:[0,1]
	v_add_f32_e32 v0, v3, v0
	v_max_f32_e32 v10, 0, v10
	v_add_f32_e32 v0, v4, v0
	v_max_f32_e32 v11, 0, v11
	v_add_f32_e32 v0, v5, v0
	v_pk_mul_f32 v[10:11], v[136:137], v[10:11] op_sel:[1,0] op_sel_hi:[0,1]
	v_add_f32_e32 v0, v6, v0
	v_max_f32_e32 v12, 0, v12
	v_add_f32_e32 v0, v7, v0
	v_max_f32_e32 v13, 0, v13
	v_pk_mul_f32 v[12:13], v[138:139], v[12:13] op_sel:[1,0] op_sel_hi:[0,1]
	v_max_f32_e32 v14, 0, v14
	v_max_f32_e32 v15, 0, v15
	v_pk_mul_f32 v[14:15], v[140:141], v[14:15] op_sel:[1,0] op_sel_hi:[0,1]
	v_cmp_gt_i32_e32 vcc, v197, v190
	s_waitcnt lgkmcnt(0)
	ds_read_b128 v[244:247], v223
	ds_read_b128 v[104:107], v224
	v_add_f32_e32 v8, 0, v8
	v_add_f32_e32 v8, v9, v8
	v_add_f32_e32 v8, v10, v8
	v_add_f32_e32 v8, v11, v8
	v_cndmask_b32_e32 v1, v0, v178, vcc
	v_cndmask_b32_e32 v2, v0, v179, vcc
	v_max_f32_e32 v189, v189, v1
	v_min_f32_e32 v188, v188, v2
	v_add_f32_e32 v8, v12, v8
	v_add_f32_e32 v8, v13, v8
	v_add_f32_e32 v8, v14, v8
	v_add_f32_e32 v8, v15, v8
	v_cmp_gt_i32_e32 vcc, v197, v191
	s_waitcnt lgkmcnt(0)
	ds_write_b128 v222, v[60:63]
	ds_write_b128 v222, v[48:51] offset:1024
	ds_write2st64_b32 v196, v0, v8 offset1:64
	v_max_f32_e32 v16, 0, v16
	v_max_f32_e32 v17, 0, v17
	v_pk_mul_f32 v[16:17], v[142:143], v[16:17] op_sel:[1,0] op_sel_hi:[0,1]
	v_cndmask_b32_e32 v1, v8, v178, vcc
	v_cndmask_b32_e32 v2, v8, v179, vcc
	v_max_f32_e32 v187, v187, v1
	v_min_f32_e32 v186, v186, v2
	v_max_f32_e32 v18, 0, v18
	v_max_f32_e32 v19, 0, v19
	v_pk_mul_f32 v[18:19], v[144:145], v[18:19] op_sel:[1,0] op_sel_hi:[0,1]
	v_max_f32_e32 v20, 0, v20
	v_max_f32_e32 v21, 0, v21
	v_pk_mul_f32 v[20:21], v[146:147], v[20:21] op_sel:[1,0] op_sel_hi:[0,1]
	v_max_f32_e32 v22, 0, v22
	v_max_f32_e32 v23, 0, v23
	v_pk_mul_f32 v[22:23], v[148:149], v[22:23] op_sel:[1,0] op_sel_hi:[0,1]
	v_add_f32_e32 v16, 0, v16
	v_max_f32_e32 v24, 0, v24
	v_add_f32_e32 v16, v17, v16
	v_max_f32_e32 v25, 0, v25
	v_add_f32_e32 v16, v18, v16
	v_pk_mul_f32 v[24:25], v[150:151], v[24:25] op_sel:[1,0] op_sel_hi:[0,1]
	v_add_f32_e32 v16, v19, v16
	v_max_f32_e32 v26, 0, v26
	v_add_f32_e32 v16, v20, v16
	v_max_f32_e32 v27, 0, v27
	v_add_f32_e32 v16, v21, v16
	v_pk_mul_f32 v[26:27], v[152:153], v[26:27] op_sel:[1,0] op_sel_hi:[0,1]
	v_add_f32_e32 v16, v22, v16
	v_max_f32_e32 v28, 0, v28
	v_add_f32_e32 v16, v23, v16
	v_max_f32_e32 v29, 0, v29
	v_pk_mul_f32 v[28:29], v[154:155], v[28:29] op_sel:[1,0] op_sel_hi:[0,1]
	v_max_f32_e32 v30, 0, v30
	v_max_f32_e32 v31, 0, v31
	v_pk_mul_f32 v[30:31], v[156:157], v[30:31] op_sel:[1,0] op_sel_hi:[0,1]
	v_cmp_gt_i32_e32 vcc, v197, v192
	v_add_u32_e32 v3, 0x10000, v196
	s_waitcnt lgkmcnt(0)
	ds_read_b128 v[100:103], v223
	ds_read_b128 v[96:99], v224
	v_add_f32_e32 v24, 0, v24
	v_add_f32_e32 v24, v25, v24
	v_add_f32_e32 v24, v26, v24
	v_add_f32_e32 v24, v27, v24
	ds_write_b32 v3, v16
	v_cndmask_b32_e32 v1, v16, v178, vcc
	v_cndmask_b32_e32 v2, v16, v179, vcc
	v_max_f32_e32 v185, v185, v1
	v_min_f32_e32 v184, v184, v2
	v_add_f32_e32 v24, v28, v24
	v_add_f32_e32 v24, v29, v24
	v_add_f32_e32 v24, v30, v24
	v_add_f32_e32 v24, v31, v24
	v_cmp_gt_i32_e32 vcc, v197, v193
	v_add_u32_e32 v3, 0x14000, v196
	v_add_u32_e32 v196, 0x400, v196
	ds_write_b32 v3, v24
	v_cndmask_b32_e32 v1, v24, v178, vcc
	v_cndmask_b32_e32 v2, v24, v179, vcc
	v_max_f32_e32 v183, v183, v1
	v_min_f32_e32 v123, v123, v2
	s_and_b64 vcc, exec, s[24:25]
	s_cbranch_vccnz .LBB0_874
	s_mov_b32 s6, s3
.Lidx_loopB:
	s_add_i32 s1, s1, 8
	s_cmp_ge_i32 s1, s0
	s_cselect_b64 s[24:25], -1, 0
	s_add_i32 s3, s6, 0x100
	s_add_i32 s32, s1, 8
	s_cmp_lt_i32 s32, s0
	s_cbranch_scc0 .Lidx_nofarB
	s_add_i32 s32, s6, 0x200
	v_mad_i64_i32 v[0:1], s[26:27], s32, v177, v[216:217]
	s_add_i32 s32, s32, 16
	v_mad_i64_i32 v[220:221], s[26:27], s32, v177, v[216:217]
	global_load_dwordx4 v[52:55], v[0:1], off
	global_load_dwordx4 v[56:59], v[220:221], off
	global_load_dwordx4 v[60:63], v[0:1], off offset:64
	global_load_dwordx4 v[48:51], v[220:221], off offset:64

; #define LAS __attribute__((address_space(3)))
; __device__ __forceinline__ void indexer_phase(const bf16_t* PJ, float* rk, unsigned short* SEL, LAS unsigned char* lds) {
;     ...
;             while (kt < nkt) {
;                 const int kn = kt + NWAVE;
;                 if (kn < nkt) {
; #pragma unroll
;                     for (int kk = 0; kk < 4; ++kk) bnxt[kk] = *(const bf16x8*)(kbase + (size_t)(32 * kn) * PROJ_LD + kk * 16);
;                 }
;                 const int key = 32 * kt + r32;
; #pragma unroll
;                 for (int rt = 0; rt < 2; ++rt) {
;                     f32x16 acc = f32x16{};
; #pragma unroll
;                     for (int kk = 0; kk < 4; ++kk) acc = __builtin_amdgcn_mfma_f32_32x32x16_bf16(af[rt][kk], bcur[kk], acc, 0, 0, 0);
; #pragma unroll
;                     for (int qq = 0; qq < 2; ++qq) { float s = 0.f;
; #pragma unroll
;                         for (int e = 0; e < 8; ++e) s += wq[rt][qq][e] * fmaxf(acc[8 * qq + e], 0.f);
;                         ((LAS float*)lds)[(4 * rt + 2 * hi + qq) * 4096 + key] = s;
;                         const bool ok = key <= t0 + 4 * rt + 2 * hi + qq;
;                         rmax[rt][qq] = fmaxf(rmax[rt][qq], ok ? s : -INFINITY); rmin[rt][qq] = fminf(rmin[rt][qq], ok ? s : INFINITY); }
.Lidx_trB:
	ds_write_b128 v222, v[228:231]
	ds_write_b128 v222, v[232:235] offset:1024
	s_nop 3
	v_max_f32_e32 v0, 0, v0
	v_max_f32_e32 v1, 0, v1
	v_pk_mul_f32 v[0:1], v[126:127], v[0:1] op_sel:[1,0] op_sel_hi:[0,1]
	v_max_f32_e32 v2, 0, v2
	v_max_f32_e32 v3, 0, v3
	v_pk_mul_f32 v[2:3], v[128:129], v[2:3] op_sel:[1,0] op_sel_hi:[0,1]
	v_max_f32_e32 v4, 0, v4
	v_max_f32_e32 v5, 0, v5
	v_pk_mul_f32 v[4:5], v[130:131], v[4:5] op_sel:[1,0] op_sel_hi:[0,1]
	v_max_f32_e32 v6, 0, v6
	v_max_f32_e32 v7, 0, v7
	v_pk_mul_f32 v[6:7], v[132:133], v[6:7] op_sel:[1,0] op_sel_hi:[0,1]
	v_add_f32_e32 v0, 0, v0
	v_max_f32_e32 v8, 0, v8
	v_add_f32_e32 v0, v1, v0
	v_max_f32_e32 v9, 0, v9
	v_add_f32_e32 v0, v2, v0
	v_pk_mul_f32 v[8:9], v[134:135], v[8:9] op_sel:[1,0] op_sel_hi:[0,1]
	v_add_f32_e32 v0, v3, v0
	v_max_f32_e32 v10, 0, v10
	v_add_f32_e32 v0, v4, v0
	v_max_f32_e32 v11, 0, v11
	v_add_f32_e32 v0, v5, v0
	v_pk_mul_f32 v[10:11], v[136:137], v[10:11] op_sel:[1,0] op_sel_hi:[0,1]
	v_add_f32_e32 v0, v6, v0
	v_max_f32_e32 v12, 0, v12
	v_add_f32_e32 v0, v7, v0
	v_max_f32_e32 v13, 0, v13
	v_pk_mul_f32 v[12:13], v[138:139], v[12:13] op_sel:[1,0] op_sel_hi:[0,1]
	v_max_f32_e32 v14, 0, v14
	v_max_f32_e32 v15, 0, v15
	v_pk_mul_f32 v[14:15], v[140:141], v[14:15] op_sel:[1,0] op_sel_hi:[0,1]
	v_cmp_gt_i32_e32 vcc, v197, v190
	s_waitcnt lgkmcnt(0)
	ds_read_b128 v[244:247], v223
	ds_read_b128 v[104:107], v224
	v_add_f32_e32 v8, 0, v8
	v_add_f32_e32 v8, v9, v8
	v_add_f32_e32 v8, v10, v8
	v_add_f32_e32 v8, v11, v8
	v_cndmask_b32_e32 v1, v0, v178, vcc
	v_cndmask_b32_e32 v2, v0, v179, vcc
	v_max_f32_e32 v189, v189, v1
	v_min_f32_e32 v188, v188, v2
	v_add_f32_e32 v8, v12, v8
	v_add_f32_e32 v8, v13, v8
	v_add_f32_e32 v8, v14, v8
	v_add_f32_e32 v8, v15, v8
	v_cmp_gt_i32_e32 vcc, v197, v191
	s_waitcnt lgkmcnt(0)
	ds_write_b128 v222, v[236:239]
	ds_write_b128 v222, v[240:243] offset:1024
	ds_write2st64_b32 v196, v0, v8 offset1:64
	v_max_f32_e32 v16, 0, v16
	v_max_f32_e32 v17, 0, v17
	v_pk_mul_f32 v[16:17], v[142:143], v[16:17] op_sel:[1,0] op_sel_hi:[0,1]
	v_cndmask_b32_e32 v1, v8, v178, vcc
	v_cndmask_b32_e32 v2, v8, v179, vcc
	v_max_f32_e32 v187, v187, v1
	v_min_f32_e32 v186, v186, v2
	v_max_f32_e32 v18, 0, v18
	v_max_f32_e32 v19, 0, v19
	v_pk_mul_f32 v[18:19], v[144:145], v[18:19] op_sel:[1,0] op_sel_hi:[0,1]
	v_max_f32_e32 v20, 0, v20
	v_max_f32_e32 v21, 0, v21
	v_pk_mul_f32 v[20:21], v[146:147], v[20:21] op_sel:[1,0] op_sel_hi:[0,1]
	v_max_f32_e32 v22, 0, v22
	v_max_f32_e32 v23, 0, v23
	v_pk_mul_f32 v[22:23], v[148:149], v[22:23] op_sel:[1,0] op_sel_hi:[0,1]
	v_add_f32_e32 v16, 0, v16
	v_max_f32_e32 v24, 0, v24
	v_add_f32_e32 v16, v17, v16
	v_max_f32_e32 v25, 0, v25
	v_add_f32_e32 v16, v18, v16
	v_pk_mul_f32 v[24:25], v[150:151], v[24:25] op_sel:[1,0] op_sel_hi:[0,1]
	v_add_f32_e32 v16, v19, v16
	v_max_f32_e32 v26, 0, v26
	v_add_f32_e32 v16, v20, v16
	v_max_f32_e32 v27, 0, v27
	v_add_f32_e32 v16, v21, v16
	v_pk_mul_f32 v[26:27], v[152:153], v[26:27] op_sel:[1,0] op_sel_hi:[0,1]
	v_add_f32_e32 v16, v22, v16
	v_max_f32_e32 v28, 0, v28
	v_add_f32_e32 v16, v23, v16
	v_max_f32_e32 v29, 0, v29
	v_pk_mul_f32 v[28:29], v[154:155], v[28:29] op_sel:[1,0] op_sel_hi:[0,1]
	v_max_f32_e32 v30, 0, v30
	v_max_f32_e32 v31, 0, v31
	v_pk_mul_f32 v[30:31], v[156:157], v[30:31] op_sel:[1,0] op_sel_hi:[0,1]
	v_cmp_gt_i32_e32 vcc, v197, v192
	v_add_u32_e32 v3, 0x10000, v196
	s_waitcnt lgkmcnt(0)
	ds_read_b128 v[100:103], v223
	ds_read_b128 v[96:99], v224
	v_add_f32_e32 v24, 0, v24
	v_add_f32_e32 v24, v25, v24
	v_add_f32_e32 v24, v26, v24
	v_add_f32_e32 v24, v27, v24
	ds_write_b32 v3, v16
	v_cndmask_b32_e32 v1, v16, v178, vcc
	v_cndmask_b32_e32 v2, v16, v179, vcc
	v_max_f32_e32 v185, v185, v1
	v_min_f32_e32 v184, v184, v2
	v_add_f32_e32 v24, v28, v24
	v_add_f32_e32 v24, v29, v24
	v_add_f32_e32 v24, v30, v24
	v_add_f32_e32 v24, v31, v24
	v_cmp_gt_i32_e32 vcc, v197, v193
	v_add_u32_e32 v3, 0x14000, v196
	v_add_u32_e32 v196, 0x400, v196
	ds_write_b32 v3, v24
	v_cndmask_b32_e32 v1, v24, v178, vcc
	v_cndmask_b32_e32 v2, v24, v179, vcc
	v_max_f32_e32 v183, v183, v1
	v_min_f32_e32 v123, v123, v2
	s_and_b64 vcc, exec, s[24:25]
	s_cbranch_vccnz .LBB0_874
	s_mov_b32 s6, s3
	s_branch .Lidx_loopA

; __device__ __forceinline__ void indexer_phase(const bf16_t* PJ, float* rk, unsigned short* SEL, LAS unsigned char* lds) {
;     ...
; #pragma unroll
;             for (int rt = 0; rt < 2; ++rt)
; #pragma unroll
;                 for (int qq = 0; qq < 2; ++qq) {
; #pragma unroll
;                     for (int o = 1; o < 32; o <<= 1) { rmax[rt][qq] = fmaxf(rmax[rt][qq], __shfl_xor(rmax[rt][qq], o)); rmin[rt][qq] = fminf(rmin[rt][qq], __shfl_xor(rmin[rt][qq], o)); }
;                     if (r32 == 0) { pmm[(wid * 8 + 4 * rt + 2 * hi + qq) * 2] = rmax[rt][qq]; pmm[(wid * 8 + 4 * rt + 2 * hi + qq) * 2 + 1] = rmin[rt][qq]; } }
.LBB0_874:
	s_waitcnt lgkmcnt(0)
	v_and_b32_e32 v11, 64, v180
	v_add_u32_e32 v0, 64, v11
	v_xor_b32_e32 v1, 1, v180
	v_cmp_lt_i32_e32 vcc, v1, v0
	v_xor_b32_e32 v4, 2, v180
	v_max_f32_e32 v3, v189, v189
	v_cndmask_b32_e32 v1, v180, v1, vcc
	v_lshlrev_b32_e32 v20, 2, v1
	ds_bpermute_b32 v1, v20, v189
	v_cmp_lt_i32_e32 vcc, v4, v0
	ds_bpermute_b32 v2, v20, v188
	s_waitcnt lgkmcnt(1)
	v_max_f32_e32 v1, v1, v1
	v_cndmask_b32_e32 v4, v180, v4, vcc
	v_max_f32_e32 v1, v3, v1
	v_lshlrev_b32_e32 v21, 2, v4
	ds_bpermute_b32 v4, v21, v1
	s_waitcnt lgkmcnt(1)
	v_max_f32_e32 v2, v2, v2
	v_max_f32_e32 v3, v188, v188
	v_min_f32_e32 v2, v3, v2
	ds_bpermute_b32 v3, v21, v2
	s_waitcnt lgkmcnt(1)
	v_max_f32_e32 v4, v4, v4
	v_max_f32_e32 v1, v1, v4
	v_xor_b32_e32 v4, 4, v180
	v_cmp_lt_i32_e32 vcc, v4, v0
	s_waitcnt lgkmcnt(0)
	v_max_f32_e32 v3, v3, v3
	v_min_f32_e32 v2, v2, v3
	v_cndmask_b32_e32 v4, v180, v4, vcc
	v_lshlrev_b32_e32 v22, 2, v4
	ds_bpermute_b32 v4, v22, v1
	ds_bpermute_b32 v3, v22, v2
	s_waitcnt lgkmcnt(1)
	v_max_f32_e32 v4, v4, v4
	v_max_f32_e32 v1, v1, v4
	v_xor_b32_e32 v4, 8, v180
	v_cmp_lt_i32_e32 vcc, v4, v0
	s_waitcnt lgkmcnt(0)
	v_max_f32_e32 v3, v3, v3
	v_min_f32_e32 v3, v2, v3
	v_cndmask_b32_e32 v4, v180, v4, vcc
	v_lshlrev_b32_e32 v23, 2, v4
	ds_bpermute_b32 v4, v23, v1
	ds_bpermute_b32 v5, v23, v3
	s_waitcnt lgkmcnt(1)
	v_max_f32_e32 v2, v4, v4
	v_max_f32_e32 v2, v1, v2
	s_waitcnt lgkmcnt(0)
	v_max_f32_e32 v1, v5, v5
	v_min_f32_e32 v1, v3, v1
	v_xor_b32_e32 v3, 16, v180
	v_cmp_lt_i32_e32 vcc, v3, v0
	s_nop 1
	v_cndmask_b32_e32 v3, v180, v3, vcc
	v_lshlrev_b32_e32 v24, 2, v3
	ds_bpermute_b32 v4, v24, v2
	ds_bpermute_b32 v3, v24, v1
	s_and_saveexec_b64 s[24:25], s[8:9]
	s_cbranch_execz .LBB0_876
	s_waitcnt lgkmcnt(0)
	v_max_f32_e32 v3, v3, v3
	v_max_f32_e32 v1, v1, v1
	v_max_f32_e32 v4, v4, v4
	v_max_f32_e32 v2, v2, v2
	v_min_f32_e32 v3, v1, v3
	v_add_u32_e32 v1, 0, v160
	v_max_f32_e32 v2, v2, v4
	v_add_u32_e32 v1, 0x26000, v1
	ds_write_b64 v1, v[2:3]
